# scan phase: chunk section re-ordered (state scale/convert, then the 8-MFMA P tile through three operand register sets with C=0 start, mask/store, then KT^T V with all operand sets read together) + out
# baseline (speedup 1.0000x reference)
; #define LAS __attribute__((address_space(3)))
; DI void phase_scan(int l, int wv, bool fill, bool last) {
;     ...
;             {   const int kb = w >> 1, vb = w & 1;
;                 const LAS float* er = (const LAS float*)(L + O_EV) + kb * 32 + 4 * hh; const LAS float* ebr = er + 128; const LAS float* eb = er + 256;
; #pragma unroll
;                 for (int g = 0; g < 4; ++g) { const f32x4 e4 = *(const LAS f32x4*)(er + 8 * g);
;                     u32x2 pk; pk.x = pk2(S[4 * g] * e4.x, S[4 * g + 1] * e4.y); pk.y = pk2(S[4 * g + 2] * e4.z, S[4 * g + 3] * e4.w);
;                     *(LAS u32x2*)(L + O_ST + (vb * 32 + r32) * RS + (kb * 32 + 8 * g + 4 * hh) * 2) = pk; }
;                 f32x16 U;
; #pragma unroll
;                 for (int i = 0; i < 16; ++i) U[i] = 0.f;
; #pragma unroll
;                 for (int ks = 0; ks < 4; ++ks) { const bf16x8v a = tr_frag(L + O_KT, RS, ks * 16 + 8 * hh, kb * 32, lane), bv = tr_frag(L + O_V, RS64, ks * 16 + 8 * hh, vb * 32, lane);
;                     U = __builtin_amdgcn_mfma_f32_32x32x16_bf16(a, bv, U, 0, 0, 0); }
; #pragma unroll
;                 for (int g = 0; g < 4; ++g) { const f32x4 b4 = *(const LAS f32x4*)(eb + 8 * g), c4 = *(const LAS f32x4*)(ebr + 8 * g);
;                     S[4 * g] = b4.x * S[4 * g] + c4.x * U[4 * g]; S[4 * g + 1] = b4.y * S[4 * g + 1] + c4.y * U[4 * g + 1]; S[4 * g + 2] = b4.z * S[4 * g + 2] + c4.z * U[4 * g + 2]; S[4 * g + 3] = b4.w * S[4 * g + 3] + c4.w * U[4 * g + 3]; }
;             }
;             const bool outp = !(last && c < 4);
;             if (w < 4 && outp) {
;                 const int tb = w >> 1, sb = w & 1;
;                 f32x16 acc;
; #pragma unroll
;                 for (int i = 0; i < 16; ++i) acc[i] = 0.f;
; #pragma unroll 4
;                 for (int ks = 0; ks < 8; ++ks) { const bf16x8v a = *(const LAS bf16x8v*)(L + O_QT + (tb * 32 + r32) * RS + (ks * 16 + 8 * hh) * 2), bq = *(const LAS bf16x8v*)(L + O_KT + (sb * 32 + r32) * RS + (ks * 16 + 8 * hh) * 2);
;                     acc = __builtin_amdgcn_mfma_f32_32x32x16_bf16(a, bq, acc, 0, 0, 0); }
; #pragma unroll
;                 for (int i = 0; i < 16; ++i) { const int t = tb * 32 + (i & 3) + 8 * (i >> 2) + 4 * hh, sp = sb * 32 + r32; const bool keep = dir ? (sp >= t) : (sp <= t);
;                     *(LAS unsigned short*)(L + O_PM + t * RS64 + sp * 2) = f2bf1(keep ? acc[i] : 0.f); }
.LBB0_494:
	s_waitcnt lgkmcnt(0)
	s_barrier
	ds_read_b128 v[88:91], v189
	ds_read_b128 v[92:95], v189 offset:32
	ds_read_b128 v[96:99], v189 offset:64
	ds_read_b128 v[100:103], v189 offset:96
	ds_read_b128 v[0:3], v194
	ds_read_b128 v[4:7], v193
	ds_read_b128 v[8:11], v194 offset:32
	ds_read_b128 v[12:15], v193 offset:32
	s_cmp_gt_u32 s78, 3
	v_readlane_b32 s62, v254, 33
	s_cselect_b64 s[60:61], -1, 0
	v_readlane_b32 s63, v254, 34
	s_waitcnt lgkmcnt(7)
	v_mul_f32_e32 v112, v168, v88
	v_mul_f32_e32 v113, v169, v89
	v_mul_f32_e32 v114, v170, v90
	v_mul_f32_e32 v115, v171, v91
	v_cvt_pk_bf16_f32 v104, v112, v113
	v_cvt_pk_bf16_f32 v105, v114, v115
	ds_write_b64 v200, v[104:105] offset:34816
	s_or_b64 s[60:61], s[62:63], s[60:61]
	s_and_b64 s[62:63], s[54:55], s[60:61]
	s_andn2_b64 vcc, exec, s[62:63]
	s_waitcnt lgkmcnt(7)
	v_mul_f32_e32 v112, v172, v92
	v_mul_f32_e32 v113, v173, v93
	v_mul_f32_e32 v114, v174, v94
	v_mul_f32_e32 v115, v175, v95
	v_cvt_pk_bf16_f32 v106, v112, v113
	v_cvt_pk_bf16_f32 v107, v114, v115
	ds_write_b64 v200, v[106:107] offset:34832
	s_waitcnt lgkmcnt(7)
	v_mul_f32_e32 v112, v176, v96
	v_mul_f32_e32 v113, v177, v97
	v_mul_f32_e32 v114, v178, v98
	v_mul_f32_e32 v115, v179, v99
	v_cvt_pk_bf16_f32 v108, v112, v113
	v_cvt_pk_bf16_f32 v109, v114, v115
	ds_write_b64 v200, v[108:109] offset:34848
	s_waitcnt lgkmcnt(7)
	v_mul_f32_e32 v112, v180, v100
	v_mul_f32_e32 v113, v181, v101
	v_mul_f32_e32 v114, v182, v102
	v_mul_f32_e32 v115, v183, v103
	v_cvt_pk_bf16_f32 v110, v112, v113
	v_cvt_pk_bf16_f32 v111, v114, v115
	ds_write_b64 v200, v[110:111] offset:34864
	s_cbranch_vccnz .Lscan_no_ptile
	ds_read_b128 v[232:235], v194 offset:64
	ds_read_b128 v[208:211], v193 offset:64
	s_waitcnt lgkmcnt(8)
	v_mfma_f32_32x32x16_bf16 v[16:31], v[0:3], v[4:7], 0
	ds_read_b128 v[0:3], v194 offset:96
	ds_read_b128 v[4:7], v193 offset:96
	s_waitcnt lgkmcnt(8)
	v_mfma_f32_32x32x16_bf16 v[16:31], v[8:11], v[12:15], v[16:31]
	ds_read_b128 v[8:11], v194 offset:128
	ds_read_b128 v[12:15], v193 offset:128
	s_waitcnt lgkmcnt(4)
	v_mfma_f32_32x32x16_bf16 v[16:31], v[232:235], v[208:211], v[16:31]
	ds_read_b128 v[232:235], v194 offset:160
	ds_read_b128 v[208:211], v193 offset:160
	s_waitcnt lgkmcnt(4)
	v_mfma_f32_32x32x16_bf16 v[16:31], v[0:3], v[4:7], v[16:31]
	ds_read_b128 v[0:3], v194 offset:192
	ds_read_b128 v[4:7], v193 offset:192
	s_waitcnt lgkmcnt(4)
	v_mfma_f32_32x32x16_bf16 v[16:31], v[8:11], v[12:15], v[16:31]
	ds_read_b128 v[8:11], v194 offset:224
	ds_read_b128 v[12:15], v193 offset:224
	s_waitcnt lgkmcnt(4)
	v_mfma_f32_32x32x16_bf16 v[16:31], v[232:235], v[208:211], v[16:31]
	s_waitcnt lgkmcnt(2)
	v_mfma_f32_32x32x16_bf16 v[16:31], v[0:3], v[4:7], v[16:31]
	s_waitcnt lgkmcnt(0)
	v_mfma_f32_32x32x16_bf16 v[16:31], v[8:11], v[12:15], v[16:31]
	s_nop 1
	s_nop 10
	v_cndmask_b32_e64 v16, 0, v16, s[12:13]
	v_cvt_pk_bf16_f32 v16, v16, v129
	v_add_u32_e32 v159, v190, v192
	ds_write_b16 v159, v16 offset:61440
	v_cndmask_b32_e64 v16, 0, v17, s[14:15]
	v_cvt_pk_bf16_f32 v16, v16, v129
	ds_write_b16 v202, v16 offset:61440
	v_cndmask_b32_e64 v16, 0, v18, s[16:17]
	v_cvt_pk_bf16_f32 v16, v16, v129
	ds_write_b16 v203, v16 offset:61440
	v_cndmask_b32_e64 v16, 0, v19, s[18:19]
	v_cvt_pk_bf16_f32 v16, v16, v129
	ds_write_b16 v204, v16 offset:61440
	v_cndmask_b32_e64 v16, 0, v20, s[20:21]
	v_cvt_pk_bf16_f32 v16, v16, v129
	ds_write_b16 v205, v16 offset:61440
	v_cndmask_b32_e64 v16, 0, v21, s[22:23]
	v_cvt_pk_bf16_f32 v16, v16, v129
	ds_write_b16 v214, v16 offset:61440
	v_cndmask_b32_e64 v16, 0, v22, s[24:25]
	v_cvt_pk_bf16_f32 v16, v16, v129
	ds_write_b16 v215, v16 offset:61440
	v_cndmask_b32_e64 v16, 0, v23, s[26:27]
	v_cvt_pk_bf16_f32 v16, v16, v129
	ds_write_b16 v216, v16 offset:61440
	v_cndmask_b32_e64 v16, 0, v24, s[28:29]
	v_cvt_pk_bf16_f32 v16, v16, v129
	ds_write_b16 v217, v16 offset:61440
	v_cndmask_b32_e64 v16, 0, v25, s[30:31]
	v_cvt_pk_bf16_f32 v16, v16, v129
	ds_write_b16 v218, v16 offset:61440
	v_cndmask_b32_e64 v16, 0, v26, s[34:35]
	v_cvt_pk_bf16_f32 v16, v16, v129
	ds_write_b16 v219, v16 offset:61440
	v_cndmask_b32_e64 v16, 0, v27, s[38:39]
	v_cvt_pk_bf16_f32 v16, v16, v129
	ds_write_b16 v220, v16 offset:61440
	v_cndmask_b32_e64 v16, 0, v28, s[2:3]
	v_cvt_pk_bf16_f32 v16, v16, v129
	ds_write_b16 v221, v16 offset:61440
	v_cndmask_b32_e64 v16, 0, v29, s[42:43]
	v_cvt_pk_bf16_f32 v16, v16, v129
	ds_write_b16 v222, v16 offset:61440
	v_cndmask_b32_e64 v16, 0, v30, s[44:45]
	v_cvt_pk_bf16_f32 v16, v16, v129
	ds_write_b16 v223, v16 offset:61440
	v_cndmask_b32_e64 v16, 0, v31, s[46:47]
	v_cvt_pk_bf16_f32 v16, v16, v129
	ds_write_b16 v224, v16 offset:61440
.Lscan_no_ptile:
	ds_read_b64_tr_b16 v[0:1], v201 offset:17408
	ds_read_b64_tr_b16 v[2:3], v201 offset:18496
	ds_read_b64_tr_b16 v[4:5], v231 offset:52224
	ds_read_b64_tr_b16 v[6:7], v231 offset:52800
	ds_read_b64_tr_b16 v[232:233], v201 offset:21760
	ds_read_b64_tr_b16 v[234:235], v201 offset:22848
	ds_read_b64_tr_b16 v[208:209], v231 offset:54528
	ds_read_b64_tr_b16 v[210:211], v231 offset:55104
	ds_read_b64_tr_b16 v[16:17], v201 offset:26112
	ds_read_b64_tr_b16 v[18:19], v201 offset:27200
	ds_read_b64_tr_b16 v[20:21], v231 offset:56832
	ds_read_b64_tr_b16 v[22:23], v231 offset:57408
	s_waitcnt lgkmcnt(8)
	v_mfma_f32_32x32x16_bf16 v[0:15], v[0:3], v[4:7], 0
	ds_read_b64_tr_b16 v[24:25], v201 offset:30464
	ds_read_b64_tr_b16 v[26:27], v201 offset:31552
	ds_read_b64_tr_b16 v[28:29], v231 offset:59136
	ds_read_b64_tr_b16 v[30:31], v231 offset:59712
	s_waitcnt lgkmcnt(8)
	v_mfma_f32_32x32x16_bf16 v[0:15], v[232:235], v[208:211], v[0:15]
	ds_read_b128 v[88:91], v189 offset:1024
	ds_read_b128 v[108:111], v189 offset:512
	ds_read_b128 v[100:103], v189 offset:544
	ds_read_b128 v[92:95], v189 offset:1056
	s_waitcnt lgkmcnt(8)
	v_mfma_f32_32x32x16_bf16 v[0:15], v[16:19], v[20:23], v[0:15]
	ds_read_b128 v[96:99], v189 offset:1088
	ds_read_b128 v[112:115], v189 offset:576
	ds_read_b128 v[104:107], v189 offset:1120
	ds_read_b128 v[116:119], v189 offset:608
	s_waitcnt lgkmcnt(8)
	v_mfma_f32_32x32x16_bf16 v[0:15], v[24:27], v[28:31], v[0:15]
